# retention-output and gMLP unit epilogues rewritten by hand the same way (DPP/permlane16 batched RMSNorm reductions, stores at the end)
# speedup vs baseline: 1.0081x; 1.0081x over previous
; #define LAS __attribute__((address_space(3)))
; __device__ __forceinline__ float bf2f(unsigned h) { return __uint_as_float(h << 16); }
; __device__ __forceinline__ unsigned cvt_pk_bf16(float lo, float hi) { unsigned r; asm volatile("v_cvt_pk_bf16_f32 %0, %1, %2" : "=v"(r) : "v"(lo), "v"(hi)); return r; }
; __device__ __forceinline__ int crow(int r, int hi) { return (r & 3) + 8 * (r >> 2) + 4 * hi; }
; __device__ __forceinline__ void gmlp_phase(const bf16_t* GU, const bf16_t* GV, const float* lng, const float* lnb, const float* wsp, const float* bsp, bf16_t* Y, lptr lds, int blk, int G, int tid_) {
;     ...
;         const LAS bf16_t* up = (const LAS bf16_t*)(lds + 65536 + ui * 32768 + (32 * tb) * 256) + r32; bf16_t* yp = Y + ((size_t)(b * SEQ + n * 128 + 32 * tb)) * DM + 1536 + g * HD + r32;
; #pragma unroll
;         for (int r = 0; r < 16; ++r) { const int tr = crow(r, hi); const float bt = btv[r];
;             float v0 = bf2f(up[tr * HD]) * (acc[0][r] + bt), v1 = bf2f(up[tr * HD + 32]) * (acc[1][r] + bt), v2 = bf2f(up[tr * HD + 64]) * (acc[2][r] + bt), v3 = bf2f(up[tr * HD + 96]) * (acc[3][r] + bt);
;             float ss = (v0 * v0 + v1 * v1) + (v2 * v2 + v3 * v3);
;             ss += __shfl_xor(ss, 1); ss += __shfl_xor(ss, 2); ss += __shfl_xor(ss, 4); ss += __shfl_xor(ss, 8); ss += __shfl_xor(ss, 16);
;             const float rs = rsqrtf(ss * (1.0f / 128.0f) + EPS);
;             v0 *= rs; v1 *= rs; v2 *= rs; v3 *= rs;
;             const float n0 = __shfl_xor(v0, 1), n1 = __shfl_xor(v1, 1), n2 = __shfl_xor(v2, 1), n3 = __shfl_xor(v3, 1);
;             if ((r32 & 1) == 0) { bf16_t* op = yp + (size_t)tr * DM;
;                 *(unsigned*)(op) = cvt_pk_bf16(v0, n0); *(unsigned*)(op + 32) = cvt_pk_bf16(v1, n1); *(unsigned*)(op + 64) = cvt_pk_bf16(v2, n2); *(unsigned*)(op + 96) = cvt_pk_bf16(v3, n3); } }
.LBB0_628:
	s_lshl_b32 s4, s29, 13
	s_add_i32 s30, s30, s4
	s_lshl_b32 s4, s28, 12
	s_or_b32 s4, s4, s27
	s_or_b32 s4, s4, s34
	s_ashr_i32 s5, s4, 31
	s_lshl_b64 s[4:5], s[4:5], 12
	s_add_u32 s4, s22, s4
	s_addc_u32 s5, s23, s5
	s_lshl_b32 s6, s26, 1
	s_add_u32 s4, s4, s6
	s_addc_u32 s5, s5, 0
	s_add_u32 s4, s4, 0x39800c00
	s_addc_u32 s5, s5, 0
	v_lshlrev_b32_e32 v162, 1, v130
	v_and_b32_e32 v136, 1, v136
	v_add_u32_e32 v138, s30, v162
	v_cmp_eq_u32_e32 vcc, 0, v136
	v_lshl_add_u32 v138, v139, 10, v138
	v_lshl_add_u32 v162, v139, 14, v162
	ds_read_u16 v140, v138
	ds_read_u16 v141, v138 offset:64
	ds_read_u16 v142, v138 offset:128
	ds_read_u16 v143, v138 offset:192
	ds_read_u16 v144, v138 offset:256
	ds_read_u16 v145, v138 offset:320
	ds_read_u16 v146, v138 offset:384
	ds_read_u16 v147, v138 offset:448
	ds_read_u16 v156, v138 offset:512
	ds_read_u16 v157, v138 offset:576
	ds_read_u16 v158, v138 offset:640
	ds_read_u16 v159, v138 offset:704
	ds_read_u16 v160, v138 offset:768
	ds_read_u16 v161, v138 offset:832
	ds_read_u16 v130, v138 offset:896
	ds_read_u16 v131, v138 offset:960
	v_pk_add_f32 v[18:19], v[18:19], v[126:127]
	v_pk_add_f32 v[2:3], v[2:3], v[126:127]
	v_pk_add_f32 v[50:51], v[50:51], v[126:127]
	v_pk_add_f32 v[34:35], v[34:35], v[126:127]
	v_pk_add_f32 v[20:21], v[20:21], v[128:129]
	v_pk_add_f32 v[4:5], v[4:5], v[128:129]
	v_pk_add_f32 v[52:53], v[52:53], v[128:129]
	v_pk_add_f32 v[36:37], v[36:37], v[128:129]
	s_waitcnt lgkmcnt(0)
	v_lshlrev_b32_e32 v140, 16, v140
	v_lshlrev_b32_e32 v141, 16, v141
	v_lshlrev_b32_e32 v142, 16, v142
	v_lshlrev_b32_e32 v143, 16, v143
	v_lshlrev_b32_e32 v144, 16, v144
	v_lshlrev_b32_e32 v145, 16, v145
	v_lshlrev_b32_e32 v146, 16, v146
	v_lshlrev_b32_e32 v147, 16, v147
	v_lshlrev_b32_e32 v156, 16, v156
	v_lshlrev_b32_e32 v157, 16, v157
	v_lshlrev_b32_e32 v158, 16, v158
	v_lshlrev_b32_e32 v159, 16, v159
	v_lshlrev_b32_e32 v160, 16, v160
	v_lshlrev_b32_e32 v161, 16, v161
	v_lshlrev_b32_e32 v130, 16, v130
	v_lshlrev_b32_e32 v131, 16, v131
	v_mul_f32_e32 v18, v18, v140
	v_mul_f32_e32 v2, v2, v141
	v_mul_f32_e32 v50, v50, v142
	v_mul_f32_e32 v34, v34, v143
	v_mul_f32_e32 v19, v19, v144
	v_mul_f32_e32 v3, v3, v145
	v_mul_f32_e32 v51, v51, v146
	v_mul_f32_e32 v35, v35, v147
	v_mul_f32_e32 v20, v20, v156
	v_mul_f32_e32 v4, v4, v157
	v_mul_f32_e32 v52, v52, v158
	v_mul_f32_e32 v36, v36, v159
	v_mul_f32_e32 v21, v21, v160
	v_mul_f32_e32 v5, v5, v161
	v_mul_f32_e32 v53, v53, v130
	v_mul_f32_e32 v37, v37, v131
	v_pk_mul_f32 v[148:149], v[18:19], v[18:19]
	v_pk_mul_f32 v[150:151], v[20:21], v[20:21]
	v_pk_fma_f32 v[148:149], v[2:3], v[2:3], v[148:149]
	v_pk_fma_f32 v[150:151], v[4:5], v[4:5], v[150:151]
	v_pk_fma_f32 v[148:149], v[50:51], v[50:51], v[148:149]
	v_pk_fma_f32 v[150:151], v[52:53], v[52:53], v[150:151]
	v_pk_fma_f32 v[148:149], v[34:35], v[34:35], v[148:149]
	v_pk_fma_f32 v[150:151], v[36:37], v[36:37], v[150:151]
	s_nop 1
	v_add_f32_dpp v148, v148, v148 quad_perm:[1,0,3,2] row_mask:0xf bank_mask:0xf
	v_add_f32_dpp v149, v149, v149 quad_perm:[1,0,3,2] row_mask:0xf bank_mask:0xf
	v_add_f32_dpp v150, v150, v150 quad_perm:[1,0,3,2] row_mask:0xf bank_mask:0xf
	v_add_f32_dpp v151, v151, v151 quad_perm:[1,0,3,2] row_mask:0xf bank_mask:0xf
	v_add_f32_dpp v148, v148, v148 quad_perm:[2,3,0,1] row_mask:0xf bank_mask:0xf
	v_add_f32_dpp v149, v149, v149 quad_perm:[2,3,0,1] row_mask:0xf bank_mask:0xf
	v_add_f32_dpp v150, v150, v150 quad_perm:[2,3,0,1] row_mask:0xf bank_mask:0xf
	v_add_f32_dpp v151, v151, v151 quad_perm:[2,3,0,1] row_mask:0xf bank_mask:0xf
	v_add_f32_dpp v148, v148, v148 row_half_mirror row_mask:0xf bank_mask:0xf
	v_add_f32_dpp v149, v149, v149 row_half_mirror row_mask:0xf bank_mask:0xf
	v_add_f32_dpp v150, v150, v150 row_half_mirror row_mask:0xf bank_mask:0xf
	v_add_f32_dpp v151, v151, v151 row_half_mirror row_mask:0xf bank_mask:0xf
	v_add_f32_dpp v148, v148, v148 row_mirror row_mask:0xf bank_mask:0xf
	v_add_f32_dpp v149, v149, v149 row_mirror row_mask:0xf bank_mask:0xf
	v_add_f32_dpp v150, v150, v150 row_mirror row_mask:0xf bank_mask:0xf
	v_add_f32_dpp v151, v151, v151 row_mirror row_mask:0xf bank_mask:0xf
	v_mov_b32_e32 v152, v148
	v_mov_b32_e32 v153, v149
	v_mov_b32_e32 v154, v150
	v_mov_b32_e32 v155, v151
	v_permlane16_swap_b32_e32 v148, v152
	v_permlane16_swap_b32_e32 v149, v153
	v_permlane16_swap_b32_e32 v150, v154
	v_permlane16_swap_b32_e32 v151, v155
	v_add_f32_e32 v148, v148, v152
	v_add_f32_e32 v149, v149, v153
	v_add_f32_e32 v150, v150, v154
	v_add_f32_e32 v151, v151, v155
	v_fmamk_f32 v148, v148, 0x3c000000, v192
	v_fmamk_f32 v149, v149, 0x3c000000, v192
	v_fmamk_f32 v150, v150, 0x3c000000, v192
	v_fmamk_f32 v151, v151, 0x3c000000, v192
	v_rsq_f32_e32 v148, v148
	v_rsq_f32_e32 v149, v149
	v_rsq_f32_e32 v150, v150
	v_rsq_f32_e32 v151, v151
	s_nop 0
	v_pk_mul_f32 v[18:19], v[18:19], v[148:149]
	v_pk_mul_f32 v[2:3], v[2:3], v[148:149]
	v_pk_mul_f32 v[50:51], v[50:51], v[148:149]
	v_pk_mul_f32 v[34:35], v[34:35], v[148:149]
	v_pk_mul_f32 v[20:21], v[20:21], v[150:151]
	v_pk_mul_f32 v[4:5], v[4:5], v[150:151]
	v_pk_mul_f32 v[52:53], v[52:53], v[150:151]
	v_pk_mul_f32 v[36:37], v[36:37], v[150:151]
	s_nop 0
	v_mov_b32_dpp v152, v18 quad_perm:[1,0,3,2] row_mask:0xf bank_mask:0xf
	v_mov_b32_dpp v153, v2 quad_perm:[1,0,3,2] row_mask:0xf bank_mask:0xf
	v_mov_b32_dpp v154, v50 quad_perm:[1,0,3,2] row_mask:0xf bank_mask:0xf
	v_mov_b32_dpp v155, v34 quad_perm:[1,0,3,2] row_mask:0xf bank_mask:0xf
	v_cvt_pk_bf16_f32 v18, v18, v152
	v_cvt_pk_bf16_f32 v2, v2, v153
	v_cvt_pk_bf16_f32 v50, v50, v154
	v_cvt_pk_bf16_f32 v34, v34, v155
	v_mov_b32_dpp v152, v19 quad_perm:[1,0,3,2] row_mask:0xf bank_mask:0xf
; #define LAS __attribute__((address_space(3)))
; __device__ __forceinline__ float bf2f(unsigned h) { return __uint_as_float(h << 16); }
; __device__ __forceinline__ unsigned cvt_pk_bf16(float lo, float hi) { unsigned r; asm volatile("v_cvt_pk_bf16_f32 %0, %1, %2" : "=v"(r) : "v"(lo), "v"(hi)); return r; }
; __device__ __forceinline__ int crow(int r, int hi) { return (r & 3) + 8 * (r >> 2) + 4 * hi; }
; __device__ __forceinline__ void gmlp_phase(const bf16_t* GU, const bf16_t* GV, const float* lng, const float* lnb, const float* wsp, const float* bsp, bf16_t* Y, lptr lds, int blk, int G, int tid_) {
;     ...
;         const LAS bf16_t* up = (const LAS bf16_t*)(lds + 65536 + ui * 32768 + (32 * tb) * 256) + r32; bf16_t* yp = Y + ((size_t)(b * SEQ + n * 128 + 32 * tb)) * DM + 1536 + g * HD + r32;
; #pragma unroll
;         for (int r = 0; r < 16; ++r) { const int tr = crow(r, hi); const float bt = btv[r];
;             float v0 = bf2f(up[tr * HD]) * (acc[0][r] + bt), v1 = bf2f(up[tr * HD + 32]) * (acc[1][r] + bt), v2 = bf2f(up[tr * HD + 64]) * (acc[2][r] + bt), v3 = bf2f(up[tr * HD + 96]) * (acc[3][r] + bt);
;             float ss = (v0 * v0 + v1 * v1) + (v2 * v2 + v3 * v3);
;             ss += __shfl_xor(ss, 1); ss += __shfl_xor(ss, 2); ss += __shfl_xor(ss, 4); ss += __shfl_xor(ss, 8); ss += __shfl_xor(ss, 16);
;             const float rs = rsqrtf(ss * (1.0f / 128.0f) + EPS);
;             v0 *= rs; v1 *= rs; v2 *= rs; v3 *= rs;
;             const float n0 = __shfl_xor(v0, 1), n1 = __shfl_xor(v1, 1), n2 = __shfl_xor(v2, 1), n3 = __shfl_xor(v3, 1);
;             if ((r32 & 1) == 0) { bf16_t* op = yp + (size_t)tr * DM;
;                 *(unsigned*)(op) = cvt_pk_bf16(v0, n0); *(unsigned*)(op + 32) = cvt_pk_bf16(v1, n1); *(unsigned*)(op + 64) = cvt_pk_bf16(v2, n2); *(unsigned*)(op + 96) = cvt_pk_bf16(v3, n3); } }
	v_mov_b32_dpp v153, v3 quad_perm:[1,0,3,2] row_mask:0xf bank_mask:0xf
	v_mov_b32_dpp v154, v51 quad_perm:[1,0,3,2] row_mask:0xf bank_mask:0xf
	v_mov_b32_dpp v155, v35 quad_perm:[1,0,3,2] row_mask:0xf bank_mask:0xf
	v_cvt_pk_bf16_f32 v19, v19, v152
	v_cvt_pk_bf16_f32 v3, v3, v153
	v_cvt_pk_bf16_f32 v51, v51, v154
	v_cvt_pk_bf16_f32 v35, v35, v155
	v_mov_b32_dpp v152, v20 quad_perm:[1,0,3,2] row_mask:0xf bank_mask:0xf
	v_mov_b32_dpp v153, v4 quad_perm:[1,0,3,2] row_mask:0xf bank_mask:0xf
	v_mov_b32_dpp v154, v52 quad_perm:[1,0,3,2] row_mask:0xf bank_mask:0xf
	v_mov_b32_dpp v155, v36 quad_perm:[1,0,3,2] row_mask:0xf bank_mask:0xf
	v_cvt_pk_bf16_f32 v20, v20, v152
	v_cvt_pk_bf16_f32 v4, v4, v153
	v_cvt_pk_bf16_f32 v52, v52, v154
	v_cvt_pk_bf16_f32 v36, v36, v155
	v_mov_b32_dpp v152, v21 quad_perm:[1,0,3,2] row_mask:0xf bank_mask:0xf
	v_mov_b32_dpp v153, v5 quad_perm:[1,0,3,2] row_mask:0xf bank_mask:0xf
	v_mov_b32_dpp v154, v53 quad_perm:[1,0,3,2] row_mask:0xf bank_mask:0xf
	v_mov_b32_dpp v155, v37 quad_perm:[1,0,3,2] row_mask:0xf bank_mask:0xf
	v_cvt_pk_bf16_f32 v21, v21, v152
	v_cvt_pk_bf16_f32 v5, v5, v153
	v_cvt_pk_bf16_f32 v53, v53, v154
	v_cvt_pk_bf16_f32 v37, v37, v155
	ds_read_u16 v140, v138 offset:2048
	ds_read_u16 v141, v138 offset:2112
	ds_read_u16 v142, v138 offset:2176
	ds_read_u16 v143, v138 offset:2240
	ds_read_u16 v144, v138 offset:2304
	ds_read_u16 v145, v138 offset:2368
	ds_read_u16 v146, v138 offset:2432
	ds_read_u16 v147, v138 offset:2496
	ds_read_u16 v156, v138 offset:2560
	ds_read_u16 v157, v138 offset:2624
	ds_read_u16 v158, v138 offset:2688
	ds_read_u16 v159, v138 offset:2752
	ds_read_u16 v160, v138 offset:2816
	ds_read_u16 v161, v138 offset:2880
	ds_read_u16 v130, v138 offset:2944
	ds_read_u16 v131, v138 offset:3008
	v_pk_add_f32 v[22:23], v[22:23], v[122:123]
	v_pk_add_f32 v[6:7], v[6:7], v[122:123]
	v_pk_add_f32 v[54:55], v[54:55], v[122:123]
	v_pk_add_f32 v[38:39], v[38:39], v[122:123]
	v_pk_add_f32 v[24:25], v[24:25], v[124:125]
	v_pk_add_f32 v[8:9], v[8:9], v[124:125]
	v_pk_add_f32 v[56:57], v[56:57], v[124:125]
	v_pk_add_f32 v[40:41], v[40:41], v[124:125]
	s_waitcnt lgkmcnt(0)
	v_lshlrev_b32_e32 v140, 16, v140
	v_lshlrev_b32_e32 v141, 16, v141
	v_lshlrev_b32_e32 v142, 16, v142
	v_lshlrev_b32_e32 v143, 16, v143
	v_lshlrev_b32_e32 v144, 16, v144
	v_lshlrev_b32_e32 v145, 16, v145
	v_lshlrev_b32_e32 v146, 16, v146
	v_lshlrev_b32_e32 v147, 16, v147
	v_lshlrev_b32_e32 v156, 16, v156
	v_lshlrev_b32_e32 v157, 16, v157
	v_lshlrev_b32_e32 v158, 16, v158
	v_lshlrev_b32_e32 v159, 16, v159
	v_lshlrev_b32_e32 v160, 16, v160
	v_lshlrev_b32_e32 v161, 16, v161
	v_lshlrev_b32_e32 v130, 16, v130
	v_lshlrev_b32_e32 v131, 16, v131
	v_mul_f32_e32 v22, v22, v140
	v_mul_f32_e32 v6, v6, v141
	v_mul_f32_e32 v54, v54, v142
	v_mul_f32_e32 v38, v38, v143
	v_mul_f32_e32 v23, v23, v144
	v_mul_f32_e32 v7, v7, v145
	v_mul_f32_e32 v55, v55, v146
	v_mul_f32_e32 v39, v39, v147
	v_mul_f32_e32 v24, v24, v156
	v_mul_f32_e32 v8, v8, v157
	v_mul_f32_e32 v56, v56, v158
	v_mul_f32_e32 v40, v40, v159
	v_mul_f32_e32 v25, v25, v160
	v_mul_f32_e32 v9, v9, v161
	v_mul_f32_e32 v57, v57, v130
	v_mul_f32_e32 v41, v41, v131
	v_pk_mul_f32 v[148:149], v[22:23], v[22:23]
	v_pk_mul_f32 v[150:151], v[24:25], v[24:25]
	v_pk_fma_f32 v[148:149], v[6:7], v[6:7], v[148:149]
	v_pk_fma_f32 v[150:151], v[8:9], v[8:9], v[150:151]
	v_pk_fma_f32 v[148:149], v[54:55], v[54:55], v[148:149]
	v_pk_fma_f32 v[150:151], v[56:57], v[56:57], v[150:151]
	v_pk_fma_f32 v[148:149], v[38:39], v[38:39], v[148:149]
	v_pk_fma_f32 v[150:151], v[40:41], v[40:41], v[150:151]
	s_nop 1
	v_add_f32_dpp v148, v148, v148 quad_perm:[1,0,3,2] row_mask:0xf bank_mask:0xf
	v_add_f32_dpp v149, v149, v149 quad_perm:[1,0,3,2] row_mask:0xf bank_mask:0xf
	v_add_f32_dpp v150, v150, v150 quad_perm:[1,0,3,2] row_mask:0xf bank_mask:0xf
	v_add_f32_dpp v151, v151, v151 quad_perm:[1,0,3,2] row_mask:0xf bank_mask:0xf
	v_add_f32_dpp v148, v148, v148 quad_perm:[2,3,0,1] row_mask:0xf bank_mask:0xf
	v_add_f32_dpp v149, v149, v149 quad_perm:[2,3,0,1] row_mask:0xf bank_mask:0xf
	v_add_f32_dpp v150, v150, v150 quad_perm:[2,3,0,1] row_mask:0xf bank_mask:0xf
	v_add_f32_dpp v151, v151, v151 quad_perm:[2,3,0,1] row_mask:0xf bank_mask:0xf
	v_add_f32_dpp v148, v148, v148 row_half_mirror row_mask:0xf bank_mask:0xf
	v_add_f32_dpp v149, v149, v149 row_half_mirror row_mask:0xf bank_mask:0xf
	v_add_f32_dpp v150, v150, v150 row_half_mirror row_mask:0xf bank_mask:0xf
	v_add_f32_dpp v151, v151, v151 row_half_mirror row_mask:0xf bank_mask:0xf
	v_add_f32_dpp v148, v148, v148 row_mirror row_mask:0xf bank_mask:0xf
	v_add_f32_dpp v149, v149, v149 row_mirror row_mask:0xf bank_mask:0xf
	v_add_f32_dpp v150, v150, v150 row_mirror row_mask:0xf bank_mask:0xf
	v_add_f32_dpp v151, v151, v151 row_mirror row_mask:0xf bank_mask:0xf
	v_mov_b32_e32 v152, v148
	v_mov_b32_e32 v153, v149
	v_mov_b32_e32 v154, v150
	v_mov_b32_e32 v155, v151
	v_permlane16_swap_b32_e32 v148, v152
	v_permlane16_swap_b32_e32 v149, v153
	v_permlane16_swap_b32_e32 v150, v154
	v_permlane16_swap_b32_e32 v151, v155
	v_add_f32_e32 v148, v148, v152
	v_add_f32_e32 v149, v149, v153
	v_add_f32_e32 v150, v150, v154
	v_add_f32_e32 v151, v151, v155
	v_fmamk_f32 v148, v148, 0x3c000000, v192
	v_fmamk_f32 v149, v149, 0x3c000000, v192
	v_fmamk_f32 v150, v150, 0x3c000000, v192
	v_fmamk_f32 v151, v151, 0x3c000000, v192
	v_rsq_f32_e32 v148, v148
	v_rsq_f32_e32 v149, v149
	v_rsq_f32_e32 v150, v150
	v_rsq_f32_e32 v151, v151
	s_nop 0
	v_pk_mul_f32 v[22:23], v[22:23], v[148:149]
	v_pk_mul_f32 v[6:7], v[6:7], v[148:149]
	v_pk_mul_f32 v[54:55], v[54:55], v[148:149]
	v_pk_mul_f32 v[38:39], v[38:39], v[148:149]
; #define LAS __attribute__((address_space(3)))
; __device__ __forceinline__ float bf2f(unsigned h) { return __uint_as_float(h << 16); }
; __device__ __forceinline__ unsigned cvt_pk_bf16(float lo, float hi) { unsigned r; asm volatile("v_cvt_pk_bf16_f32 %0, %1, %2" : "=v"(r) : "v"(lo), "v"(hi)); return r; }
; __device__ __forceinline__ int crow(int r, int hi) { return (r & 3) + 8 * (r >> 2) + 4 * hi; }
; __device__ __forceinline__ void gmlp_phase(const bf16_t* GU, const bf16_t* GV, const float* lng, const float* lnb, const float* wsp, const float* bsp, bf16_t* Y, lptr lds, int blk, int G, int tid_) {
;     ...
;         const LAS bf16_t* up = (const LAS bf16_t*)(lds + 65536 + ui * 32768 + (32 * tb) * 256) + r32; bf16_t* yp = Y + ((size_t)(b * SEQ + n * 128 + 32 * tb)) * DM + 1536 + g * HD + r32;
; #pragma unroll
;         for (int r = 0; r < 16; ++r) { const int tr = crow(r, hi); const float bt = btv[r];
;             float v0 = bf2f(up[tr * HD]) * (acc[0][r] + bt), v1 = bf2f(up[tr * HD + 32]) * (acc[1][r] + bt), v2 = bf2f(up[tr * HD + 64]) * (acc[2][r] + bt), v3 = bf2f(up[tr * HD + 96]) * (acc[3][r] + bt);
;             float ss = (v0 * v0 + v1 * v1) + (v2 * v2 + v3 * v3);
;             ss += __shfl_xor(ss, 1); ss += __shfl_xor(ss, 2); ss += __shfl_xor(ss, 4); ss += __shfl_xor(ss, 8); ss += __shfl_xor(ss, 16);
;             const float rs = rsqrtf(ss * (1.0f / 128.0f) + EPS);
;             v0 *= rs; v1 *= rs; v2 *= rs; v3 *= rs;
;             const float n0 = __shfl_xor(v0, 1), n1 = __shfl_xor(v1, 1), n2 = __shfl_xor(v2, 1), n3 = __shfl_xor(v3, 1);
;             if ((r32 & 1) == 0) { bf16_t* op = yp + (size_t)tr * DM;
;                 *(unsigned*)(op) = cvt_pk_bf16(v0, n0); *(unsigned*)(op + 32) = cvt_pk_bf16(v1, n1); *(unsigned*)(op + 64) = cvt_pk_bf16(v2, n2); *(unsigned*)(op + 96) = cvt_pk_bf16(v3, n3); } }
	v_pk_mul_f32 v[24:25], v[24:25], v[150:151]
	v_pk_mul_f32 v[8:9], v[8:9], v[150:151]
	v_pk_mul_f32 v[56:57], v[56:57], v[150:151]
	v_pk_mul_f32 v[40:41], v[40:41], v[150:151]
	s_nop 0
	v_mov_b32_dpp v152, v22 quad_perm:[1,0,3,2] row_mask:0xf bank_mask:0xf
	v_mov_b32_dpp v153, v6 quad_perm:[1,0,3,2] row_mask:0xf bank_mask:0xf
	v_mov_b32_dpp v154, v54 quad_perm:[1,0,3,2] row_mask:0xf bank_mask:0xf
	v_mov_b32_dpp v155, v38 quad_perm:[1,0,3,2] row_mask:0xf bank_mask:0xf
	v_cvt_pk_bf16_f32 v22, v22, v152
	v_cvt_pk_bf16_f32 v6, v6, v153
	v_cvt_pk_bf16_f32 v54, v54, v154
	v_cvt_pk_bf16_f32 v38, v38, v155
	v_mov_b32_dpp v152, v23 quad_perm:[1,0,3,2] row_mask:0xf bank_mask:0xf
	v_mov_b32_dpp v153, v7 quad_perm:[1,0,3,2] row_mask:0xf bank_mask:0xf
	v_mov_b32_dpp v154, v55 quad_perm:[1,0,3,2] row_mask:0xf bank_mask:0xf
	v_mov_b32_dpp v155, v39 quad_perm:[1,0,3,2] row_mask:0xf bank_mask:0xf
	v_cvt_pk_bf16_f32 v23, v23, v152
	v_cvt_pk_bf16_f32 v7, v7, v153
	v_cvt_pk_bf16_f32 v55, v55, v154
	v_cvt_pk_bf16_f32 v39, v39, v155
	v_mov_b32_dpp v152, v24 quad_perm:[1,0,3,2] row_mask:0xf bank_mask:0xf
	v_mov_b32_dpp v153, v8 quad_perm:[1,0,3,2] row_mask:0xf bank_mask:0xf
	v_mov_b32_dpp v154, v56 quad_perm:[1,0,3,2] row_mask:0xf bank_mask:0xf
	v_mov_b32_dpp v155, v40 quad_perm:[1,0,3,2] row_mask:0xf bank_mask:0xf
	v_cvt_pk_bf16_f32 v24, v24, v152
	v_cvt_pk_bf16_f32 v8, v8, v153
	v_cvt_pk_bf16_f32 v56, v56, v154
	v_cvt_pk_bf16_f32 v40, v40, v155
	v_mov_b32_dpp v152, v25 quad_perm:[1,0,3,2] row_mask:0xf bank_mask:0xf
	v_mov_b32_dpp v153, v9 quad_perm:[1,0,3,2] row_mask:0xf bank_mask:0xf
	v_mov_b32_dpp v154, v57 quad_perm:[1,0,3,2] row_mask:0xf bank_mask:0xf
	v_mov_b32_dpp v155, v41 quad_perm:[1,0,3,2] row_mask:0xf bank_mask:0xf
	v_cvt_pk_bf16_f32 v25, v25, v152
	v_cvt_pk_bf16_f32 v9, v9, v153
	v_cvt_pk_bf16_f32 v57, v57, v154
	v_cvt_pk_bf16_f32 v41, v41, v155
	ds_read_u16 v140, v138 offset:4096
	ds_read_u16 v141, v138 offset:4160
	ds_read_u16 v142, v138 offset:4224
	ds_read_u16 v143, v138 offset:4288
	ds_read_u16 v144, v138 offset:4352
	ds_read_u16 v145, v138 offset:4416
	ds_read_u16 v146, v138 offset:4480
	ds_read_u16 v147, v138 offset:4544
	ds_read_u16 v156, v138 offset:4608
	ds_read_u16 v157, v138 offset:4672
	ds_read_u16 v158, v138 offset:4736
	ds_read_u16 v159, v138 offset:4800
	ds_read_u16 v160, v138 offset:4864
	ds_read_u16 v161, v138 offset:4928
	ds_read_u16 v130, v138 offset:4992
	ds_read_u16 v131, v138 offset:5056
	v_pk_add_f32 v[26:27], v[26:27], v[118:119]
	v_pk_add_f32 v[10:11], v[10:11], v[118:119]
	v_pk_add_f32 v[58:59], v[58:59], v[118:119]
	v_pk_add_f32 v[42:43], v[42:43], v[118:119]
	v_pk_add_f32 v[28:29], v[28:29], v[120:121]
	v_pk_add_f32 v[12:13], v[12:13], v[120:121]
	v_pk_add_f32 v[60:61], v[60:61], v[120:121]
	v_pk_add_f32 v[44:45], v[44:45], v[120:121]
	s_waitcnt lgkmcnt(0)
	v_lshlrev_b32_e32 v140, 16, v140
	v_lshlrev_b32_e32 v141, 16, v141
	v_lshlrev_b32_e32 v142, 16, v142
	v_lshlrev_b32_e32 v143, 16, v143
	v_lshlrev_b32_e32 v144, 16, v144
	v_lshlrev_b32_e32 v145, 16, v145
	v_lshlrev_b32_e32 v146, 16, v146
	v_lshlrev_b32_e32 v147, 16, v147
	v_lshlrev_b32_e32 v156, 16, v156
	v_lshlrev_b32_e32 v157, 16, v157
	v_lshlrev_b32_e32 v158, 16, v158
	v_lshlrev_b32_e32 v159, 16, v159
	v_lshlrev_b32_e32 v160, 16, v160
	v_lshlrev_b32_e32 v161, 16, v161
	v_lshlrev_b32_e32 v130, 16, v130
	v_lshlrev_b32_e32 v131, 16, v131
	v_mul_f32_e32 v26, v26, v140
	v_mul_f32_e32 v10, v10, v141
	v_mul_f32_e32 v58, v58, v142
	v_mul_f32_e32 v42, v42, v143
	v_mul_f32_e32 v27, v27, v144
	v_mul_f32_e32 v11, v11, v145
	v_mul_f32_e32 v59, v59, v146
	v_mul_f32_e32 v43, v43, v147
	v_mul_f32_e32 v28, v28, v156
	v_mul_f32_e32 v12, v12, v157
	v_mul_f32_e32 v60, v60, v158
	v_mul_f32_e32 v44, v44, v159
	v_mul_f32_e32 v29, v29, v160
	v_mul_f32_e32 v13, v13, v161
	v_mul_f32_e32 v61, v61, v130
	v_mul_f32_e32 v45, v45, v131
	v_pk_mul_f32 v[148:149], v[26:27], v[26:27]
	v_pk_mul_f32 v[150:151], v[28:29], v[28:29]
	v_pk_fma_f32 v[148:149], v[10:11], v[10:11], v[148:149]
	v_pk_fma_f32 v[150:151], v[12:13], v[12:13], v[150:151]
	v_pk_fma_f32 v[148:149], v[58:59], v[58:59], v[148:149]
	v_pk_fma_f32 v[150:151], v[60:61], v[60:61], v[150:151]
	v_pk_fma_f32 v[148:149], v[42:43], v[42:43], v[148:149]
	v_pk_fma_f32 v[150:151], v[44:45], v[44:45], v[150:151]
	s_nop 1
	v_add_f32_dpp v148, v148, v148 quad_perm:[1,0,3,2] row_mask:0xf bank_mask:0xf
	v_add_f32_dpp v149, v149, v149 quad_perm:[1,0,3,2] row_mask:0xf bank_mask:0xf
	v_add_f32_dpp v150, v150, v150 quad_perm:[1,0,3,2] row_mask:0xf bank_mask:0xf
	v_add_f32_dpp v151, v151, v151 quad_perm:[1,0,3,2] row_mask:0xf bank_mask:0xf
	v_add_f32_dpp v148, v148, v148 quad_perm:[2,3,0,1] row_mask:0xf bank_mask:0xf
	v_add_f32_dpp v149, v149, v149 quad_perm:[2,3,0,1] row_mask:0xf bank_mask:0xf
	v_add_f32_dpp v150, v150, v150 quad_perm:[2,3,0,1] row_mask:0xf bank_mask:0xf
	v_add_f32_dpp v151, v151, v151 quad_perm:[2,3,0,1] row_mask:0xf bank_mask:0xf
	v_add_f32_dpp v148, v148, v148 row_half_mirror row_mask:0xf bank_mask:0xf
	v_add_f32_dpp v149, v149, v149 row_half_mirror row_mask:0xf bank_mask:0xf
	v_add_f32_dpp v150, v150, v150 row_half_mirror row_mask:0xf bank_mask:0xf
	v_add_f32_dpp v151, v151, v151 row_half_mirror row_mask:0xf bank_mask:0xf
	v_add_f32_dpp v148, v148, v148 row_mirror row_mask:0xf bank_mask:0xf
	v_add_f32_dpp v149, v149, v149 row_mirror row_mask:0xf bank_mask:0xf
	v_add_f32_dpp v150, v150, v150 row_mirror row_mask:0xf bank_mask:0xf
	v_add_f32_dpp v151, v151, v151 row_mirror row_mask:0xf bank_mask:0xf
	v_mov_b32_e32 v152, v148
	v_mov_b32_e32 v153, v149
	v_mov_b32_e32 v154, v150
	v_mov_b32_e32 v155, v151
	v_permlane16_swap_b32_e32 v148, v152
; #define LAS __attribute__((address_space(3)))
; __device__ __forceinline__ float bf2f(unsigned h) { return __uint_as_float(h << 16); }
; __device__ __forceinline__ unsigned cvt_pk_bf16(float lo, float hi) { unsigned r; asm volatile("v_cvt_pk_bf16_f32 %0, %1, %2" : "=v"(r) : "v"(lo), "v"(hi)); return r; }
; __device__ __forceinline__ int crow(int r, int hi) { return (r & 3) + 8 * (r >> 2) + 4 * hi; }
; __device__ __forceinline__ void gmlp_phase(const bf16_t* GU, const bf16_t* GV, const float* lng, const float* lnb, const float* wsp, const float* bsp, bf16_t* Y, lptr lds, int blk, int G, int tid_) {
;     ...
;         const LAS bf16_t* up = (const LAS bf16_t*)(lds + 65536 + ui * 32768 + (32 * tb) * 256) + r32; bf16_t* yp = Y + ((size_t)(b * SEQ + n * 128 + 32 * tb)) * DM + 1536 + g * HD + r32;
; #pragma unroll
;         for (int r = 0; r < 16; ++r) { const int tr = crow(r, hi); const float bt = btv[r];
;             float v0 = bf2f(up[tr * HD]) * (acc[0][r] + bt), v1 = bf2f(up[tr * HD + 32]) * (acc[1][r] + bt), v2 = bf2f(up[tr * HD + 64]) * (acc[2][r] + bt), v3 = bf2f(up[tr * HD + 96]) * (acc[3][r] + bt);
;             float ss = (v0 * v0 + v1 * v1) + (v2 * v2 + v3 * v3);
;             ss += __shfl_xor(ss, 1); ss += __shfl_xor(ss, 2); ss += __shfl_xor(ss, 4); ss += __shfl_xor(ss, 8); ss += __shfl_xor(ss, 16);
;             const float rs = rsqrtf(ss * (1.0f / 128.0f) + EPS);
;             v0 *= rs; v1 *= rs; v2 *= rs; v3 *= rs;
;             const float n0 = __shfl_xor(v0, 1), n1 = __shfl_xor(v1, 1), n2 = __shfl_xor(v2, 1), n3 = __shfl_xor(v3, 1);
;             if ((r32 & 1) == 0) { bf16_t* op = yp + (size_t)tr * DM;
;                 *(unsigned*)(op) = cvt_pk_bf16(v0, n0); *(unsigned*)(op + 32) = cvt_pk_bf16(v1, n1); *(unsigned*)(op + 64) = cvt_pk_bf16(v2, n2); *(unsigned*)(op + 96) = cvt_pk_bf16(v3, n3); } }
	v_permlane16_swap_b32_e32 v149, v153
	v_permlane16_swap_b32_e32 v150, v154
	v_permlane16_swap_b32_e32 v151, v155
	v_add_f32_e32 v148, v148, v152
	v_add_f32_e32 v149, v149, v153
	v_add_f32_e32 v150, v150, v154
	v_add_f32_e32 v151, v151, v155
	v_fmamk_f32 v148, v148, 0x3c000000, v192
	v_fmamk_f32 v149, v149, 0x3c000000, v192
	v_fmamk_f32 v150, v150, 0x3c000000, v192
	v_fmamk_f32 v151, v151, 0x3c000000, v192
	v_rsq_f32_e32 v148, v148
	v_rsq_f32_e32 v149, v149
	v_rsq_f32_e32 v150, v150
	v_rsq_f32_e32 v151, v151
	s_nop 0
	v_pk_mul_f32 v[26:27], v[26:27], v[148:149]
	v_pk_mul_f32 v[10:11], v[10:11], v[148:149]
	v_pk_mul_f32 v[58:59], v[58:59], v[148:149]
	v_pk_mul_f32 v[42:43], v[42:43], v[148:149]
	v_pk_mul_f32 v[28:29], v[28:29], v[150:151]
	v_pk_mul_f32 v[12:13], v[12:13], v[150:151]
	v_pk_mul_f32 v[60:61], v[60:61], v[150:151]
	v_pk_mul_f32 v[44:45], v[44:45], v[150:151]
	s_nop 0
	v_mov_b32_dpp v152, v26 quad_perm:[1,0,3,2] row_mask:0xf bank_mask:0xf
	v_mov_b32_dpp v153, v10 quad_perm:[1,0,3,2] row_mask:0xf bank_mask:0xf
	v_mov_b32_dpp v154, v58 quad_perm:[1,0,3,2] row_mask:0xf bank_mask:0xf
	v_mov_b32_dpp v155, v42 quad_perm:[1,0,3,2] row_mask:0xf bank_mask:0xf
	v_cvt_pk_bf16_f32 v26, v26, v152
	v_cvt_pk_bf16_f32 v10, v10, v153
	v_cvt_pk_bf16_f32 v58, v58, v154
	v_cvt_pk_bf16_f32 v42, v42, v155
	v_mov_b32_dpp v152, v27 quad_perm:[1,0,3,2] row_mask:0xf bank_mask:0xf
	v_mov_b32_dpp v153, v11 quad_perm:[1,0,3,2] row_mask:0xf bank_mask:0xf
	v_mov_b32_dpp v154, v59 quad_perm:[1,0,3,2] row_mask:0xf bank_mask:0xf
	v_mov_b32_dpp v155, v43 quad_perm:[1,0,3,2] row_mask:0xf bank_mask:0xf
	v_cvt_pk_bf16_f32 v27, v27, v152
	v_cvt_pk_bf16_f32 v11, v11, v153
	v_cvt_pk_bf16_f32 v59, v59, v154
	v_cvt_pk_bf16_f32 v43, v43, v155
	v_mov_b32_dpp v152, v28 quad_perm:[1,0,3,2] row_mask:0xf bank_mask:0xf
	v_mov_b32_dpp v153, v12 quad_perm:[1,0,3,2] row_mask:0xf bank_mask:0xf
	v_mov_b32_dpp v154, v60 quad_perm:[1,0,3,2] row_mask:0xf bank_mask:0xf
	v_mov_b32_dpp v155, v44 quad_perm:[1,0,3,2] row_mask:0xf bank_mask:0xf
	v_cvt_pk_bf16_f32 v28, v28, v152
	v_cvt_pk_bf16_f32 v12, v12, v153
	v_cvt_pk_bf16_f32 v60, v60, v154
	v_cvt_pk_bf16_f32 v44, v44, v155
	v_mov_b32_dpp v152, v29 quad_perm:[1,0,3,2] row_mask:0xf bank_mask:0xf
	v_mov_b32_dpp v153, v13 quad_perm:[1,0,3,2] row_mask:0xf bank_mask:0xf
	v_mov_b32_dpp v154, v61 quad_perm:[1,0,3,2] row_mask:0xf bank_mask:0xf
	v_mov_b32_dpp v155, v45 quad_perm:[1,0,3,2] row_mask:0xf bank_mask:0xf
	v_cvt_pk_bf16_f32 v29, v29, v152
	v_cvt_pk_bf16_f32 v13, v13, v153
	v_cvt_pk_bf16_f32 v61, v61, v154
	v_cvt_pk_bf16_f32 v45, v45, v155
	ds_read_u16 v140, v138 offset:6144
	ds_read_u16 v141, v138 offset:6208
	ds_read_u16 v142, v138 offset:6272
	ds_read_u16 v143, v138 offset:6336
	ds_read_u16 v144, v138 offset:6400
	ds_read_u16 v145, v138 offset:6464
	ds_read_u16 v146, v138 offset:6528
	ds_read_u16 v147, v138 offset:6592
	ds_read_u16 v156, v138 offset:6656
	ds_read_u16 v157, v138 offset:6720
	ds_read_u16 v158, v138 offset:6784
	ds_read_u16 v159, v138 offset:6848
	ds_read_u16 v160, v138 offset:6912
	ds_read_u16 v161, v138 offset:6976
	ds_read_u16 v130, v138 offset:7040
	ds_read_u16 v131, v138 offset:7104
	v_pk_add_f32 v[30:31], v[30:31], v[114:115]
	v_pk_add_f32 v[14:15], v[14:15], v[114:115]
	v_pk_add_f32 v[62:63], v[62:63], v[114:115]
	v_pk_add_f32 v[46:47], v[46:47], v[114:115]
	v_pk_add_f32 v[32:33], v[32:33], v[116:117]
	v_pk_add_f32 v[16:17], v[16:17], v[116:117]
	v_pk_add_f32 v[64:65], v[64:65], v[116:117]
	v_pk_add_f32 v[48:49], v[48:49], v[116:117]
	s_waitcnt lgkmcnt(0)
	v_lshlrev_b32_e32 v140, 16, v140
	v_lshlrev_b32_e32 v141, 16, v141
	v_lshlrev_b32_e32 v142, 16, v142
	v_lshlrev_b32_e32 v143, 16, v143
	v_lshlrev_b32_e32 v144, 16, v144
	v_lshlrev_b32_e32 v145, 16, v145
	v_lshlrev_b32_e32 v146, 16, v146
	v_lshlrev_b32_e32 v147, 16, v147
	v_lshlrev_b32_e32 v156, 16, v156
	v_lshlrev_b32_e32 v157, 16, v157
	v_lshlrev_b32_e32 v158, 16, v158
	v_lshlrev_b32_e32 v159, 16, v159
	v_lshlrev_b32_e32 v160, 16, v160
	v_lshlrev_b32_e32 v161, 16, v161
	v_lshlrev_b32_e32 v130, 16, v130
	v_lshlrev_b32_e32 v131, 16, v131
	v_mul_f32_e32 v30, v30, v140
	v_mul_f32_e32 v14, v14, v141
	v_mul_f32_e32 v62, v62, v142
	v_mul_f32_e32 v46, v46, v143
	v_mul_f32_e32 v31, v31, v144
	v_mul_f32_e32 v15, v15, v145
	v_mul_f32_e32 v63, v63, v146
	v_mul_f32_e32 v47, v47, v147
	v_mul_f32_e32 v32, v32, v156
	v_mul_f32_e32 v16, v16, v157
	v_mul_f32_e32 v64, v64, v158
	v_mul_f32_e32 v48, v48, v159
	v_mul_f32_e32 v33, v33, v160
	v_mul_f32_e32 v17, v17, v161
	v_mul_f32_e32 v65, v65, v130
	v_mul_f32_e32 v49, v49, v131
	v_pk_mul_f32 v[148:149], v[30:31], v[30:31]
	v_pk_mul_f32 v[150:151], v[32:33], v[32:33]
	v_pk_fma_f32 v[148:149], v[14:15], v[14:15], v[148:149]
	v_pk_fma_f32 v[150:151], v[16:17], v[16:17], v[150:151]
	v_pk_fma_f32 v[148:149], v[62:63], v[62:63], v[148:149]
	v_pk_fma_f32 v[150:151], v[64:65], v[64:65], v[150:151]
	v_pk_fma_f32 v[148:149], v[46:47], v[46:47], v[148:149]
	v_pk_fma_f32 v[150:151], v[48:49], v[48:49], v[150:151]
	s_nop 1
	v_add_f32_dpp v148, v148, v148 quad_perm:[1,0,3,2] row_mask:0xf bank_mask:0xf
	v_add_f32_dpp v149, v149, v149 quad_perm:[1,0,3,2] row_mask:0xf bank_mask:0xf
	v_add_f32_dpp v150, v150, v150 quad_perm:[1,0,3,2] row_mask:0xf bank_mask:0xf
	v_add_f32_dpp v151, v151, v151 quad_perm:[1,0,3,2] row_mask:0xf bank_mask:0xf
	v_add_f32_dpp v148, v148, v148 quad_perm:[2,3,0,1] row_mask:0xf bank_mask:0xf
	v_add_f32_dpp v149, v149, v149 quad_perm:[2,3,0,1] row_mask:0xf bank_mask:0xf
	v_add_f32_dpp v150, v150, v150 quad_perm:[2,3,0,1] row_mask:0xf bank_mask:0xf
	v_add_f32_dpp v151, v151, v151 quad_perm:[2,3,0,1] row_mask:0xf bank_mask:0xf
; #define LAS __attribute__((address_space(3)))
; __device__ __forceinline__ float bf2f(unsigned h) { return __uint_as_float(h << 16); }
; __device__ __forceinline__ unsigned cvt_pk_bf16(float lo, float hi) { unsigned r; asm volatile("v_cvt_pk_bf16_f32 %0, %1, %2" : "=v"(r) : "v"(lo), "v"(hi)); return r; }
; __device__ __forceinline__ int crow(int r, int hi) { return (r & 3) + 8 * (r >> 2) + 4 * hi; }
; __device__ __forceinline__ void gmlp_phase(const bf16_t* GU, const bf16_t* GV, const float* lng, const float* lnb, const float* wsp, const float* bsp, bf16_t* Y, lptr lds, int blk, int G, int tid_) {
;     ...
;         const LAS bf16_t* up = (const LAS bf16_t*)(lds + 65536 + ui * 32768 + (32 * tb) * 256) + r32; bf16_t* yp = Y + ((size_t)(b * SEQ + n * 128 + 32 * tb)) * DM + 1536 + g * HD + r32;
; #pragma unroll
;         for (int r = 0; r < 16; ++r) { const int tr = crow(r, hi); const float bt = btv[r];
;             float v0 = bf2f(up[tr * HD]) * (acc[0][r] + bt), v1 = bf2f(up[tr * HD + 32]) * (acc[1][r] + bt), v2 = bf2f(up[tr * HD + 64]) * (acc[2][r] + bt), v3 = bf2f(up[tr * HD + 96]) * (acc[3][r] + bt);
;             float ss = (v0 * v0 + v1 * v1) + (v2 * v2 + v3 * v3);
;             ss += __shfl_xor(ss, 1); ss += __shfl_xor(ss, 2); ss += __shfl_xor(ss, 4); ss += __shfl_xor(ss, 8); ss += __shfl_xor(ss, 16);
;             const float rs = rsqrtf(ss * (1.0f / 128.0f) + EPS);
;             v0 *= rs; v1 *= rs; v2 *= rs; v3 *= rs;
;             const float n0 = __shfl_xor(v0, 1), n1 = __shfl_xor(v1, 1), n2 = __shfl_xor(v2, 1), n3 = __shfl_xor(v3, 1);
;             if ((r32 & 1) == 0) { bf16_t* op = yp + (size_t)tr * DM;
;                 *(unsigned*)(op) = cvt_pk_bf16(v0, n0); *(unsigned*)(op + 32) = cvt_pk_bf16(v1, n1); *(unsigned*)(op + 64) = cvt_pk_bf16(v2, n2); *(unsigned*)(op + 96) = cvt_pk_bf16(v3, n3); } }
	v_add_f32_dpp v148, v148, v148 row_half_mirror row_mask:0xf bank_mask:0xf
	v_add_f32_dpp v149, v149, v149 row_half_mirror row_mask:0xf bank_mask:0xf
	v_add_f32_dpp v150, v150, v150 row_half_mirror row_mask:0xf bank_mask:0xf
	v_add_f32_dpp v151, v151, v151 row_half_mirror row_mask:0xf bank_mask:0xf
	v_add_f32_dpp v148, v148, v148 row_mirror row_mask:0xf bank_mask:0xf
	v_add_f32_dpp v149, v149, v149 row_mirror row_mask:0xf bank_mask:0xf
	v_add_f32_dpp v150, v150, v150 row_mirror row_mask:0xf bank_mask:0xf
	v_add_f32_dpp v151, v151, v151 row_mirror row_mask:0xf bank_mask:0xf
	v_mov_b32_e32 v152, v148
	v_mov_b32_e32 v153, v149
	v_mov_b32_e32 v154, v150
	v_mov_b32_e32 v155, v151
	v_permlane16_swap_b32_e32 v148, v152
	v_permlane16_swap_b32_e32 v149, v153
	v_permlane16_swap_b32_e32 v150, v154
	v_permlane16_swap_b32_e32 v151, v155
	v_add_f32_e32 v148, v148, v152
	v_add_f32_e32 v149, v149, v153
	v_add_f32_e32 v150, v150, v154
	v_add_f32_e32 v151, v151, v155
	v_fmamk_f32 v148, v148, 0x3c000000, v192
	v_fmamk_f32 v149, v149, 0x3c000000, v192
	v_fmamk_f32 v150, v150, 0x3c000000, v192
	v_fmamk_f32 v151, v151, 0x3c000000, v192
	v_rsq_f32_e32 v148, v148
	v_rsq_f32_e32 v149, v149
	v_rsq_f32_e32 v150, v150
	v_rsq_f32_e32 v151, v151
	s_nop 0
	v_pk_mul_f32 v[30:31], v[30:31], v[148:149]
	v_pk_mul_f32 v[14:15], v[14:15], v[148:149]
	v_pk_mul_f32 v[62:63], v[62:63], v[148:149]
	v_pk_mul_f32 v[46:47], v[46:47], v[148:149]
	v_pk_mul_f32 v[32:33], v[32:33], v[150:151]
	v_pk_mul_f32 v[16:17], v[16:17], v[150:151]
	v_pk_mul_f32 v[64:65], v[64:65], v[150:151]
	v_pk_mul_f32 v[48:49], v[48:49], v[150:151]
	s_nop 0
	v_mov_b32_dpp v152, v30 quad_perm:[1,0,3,2] row_mask:0xf bank_mask:0xf
	v_mov_b32_dpp v153, v14 quad_perm:[1,0,3,2] row_mask:0xf bank_mask:0xf
	v_mov_b32_dpp v154, v62 quad_perm:[1,0,3,2] row_mask:0xf bank_mask:0xf
	v_mov_b32_dpp v155, v46 quad_perm:[1,0,3,2] row_mask:0xf bank_mask:0xf
	v_cvt_pk_bf16_f32 v30, v30, v152
	v_cvt_pk_bf16_f32 v14, v14, v153
	v_cvt_pk_bf16_f32 v62, v62, v154
	v_cvt_pk_bf16_f32 v46, v46, v155
	v_mov_b32_dpp v152, v31 quad_perm:[1,0,3,2] row_mask:0xf bank_mask:0xf
	v_mov_b32_dpp v153, v15 quad_perm:[1,0,3,2] row_mask:0xf bank_mask:0xf
	v_mov_b32_dpp v154, v63 quad_perm:[1,0,3,2] row_mask:0xf bank_mask:0xf
	v_mov_b32_dpp v155, v47 quad_perm:[1,0,3,2] row_mask:0xf bank_mask:0xf
	v_cvt_pk_bf16_f32 v31, v31, v152
	v_cvt_pk_bf16_f32 v15, v15, v153
	v_cvt_pk_bf16_f32 v63, v63, v154
	v_cvt_pk_bf16_f32 v47, v47, v155
	v_mov_b32_dpp v152, v32 quad_perm:[1,0,3,2] row_mask:0xf bank_mask:0xf
	v_mov_b32_dpp v153, v16 quad_perm:[1,0,3,2] row_mask:0xf bank_mask:0xf
	v_mov_b32_dpp v154, v64 quad_perm:[1,0,3,2] row_mask:0xf bank_mask:0xf
	v_mov_b32_dpp v155, v48 quad_perm:[1,0,3,2] row_mask:0xf bank_mask:0xf
	v_cvt_pk_bf16_f32 v32, v32, v152
	v_cvt_pk_bf16_f32 v16, v16, v153
	v_cvt_pk_bf16_f32 v64, v64, v154
	v_cvt_pk_bf16_f32 v48, v48, v155
	v_mov_b32_dpp v152, v33 quad_perm:[1,0,3,2] row_mask:0xf bank_mask:0xf
	v_mov_b32_dpp v153, v17 quad_perm:[1,0,3,2] row_mask:0xf bank_mask:0xf
	v_mov_b32_dpp v154, v65 quad_perm:[1,0,3,2] row_mask:0xf bank_mask:0xf
	v_mov_b32_dpp v155, v49 quad_perm:[1,0,3,2] row_mask:0xf bank_mask:0xf
	v_cvt_pk_bf16_f32 v33, v33, v152
	v_cvt_pk_bf16_f32 v17, v17, v153
	v_cvt_pk_bf16_f32 v65, v65, v154
	v_cvt_pk_bf16_f32 v49, v49, v155
	s_mov_b64 exec, vcc
	global_store_dword v162, v18, s[4:5]
	global_store_dword v162, v2, s[4:5] offset:64
	global_store_dword v162, v50, s[4:5] offset:128
	global_store_dword v162, v34, s[4:5] offset:192
	s_add_u32 s4, s4, 0x1000
	s_addc_u32 s5, s5, 0
	global_store_dword v162, v19, s[4:5]
	global_store_dword v162, v3, s[4:5] offset:64
	global_store_dword v162, v51, s[4:5] offset:128
	global_store_dword v162, v35, s[4:5] offset:192
	s_add_u32 s4, s4, 0x1000
	s_addc_u32 s5, s5, 0
	global_store_dword v162, v20, s[4:5]
	global_store_dword v162, v4, s[4:5] offset:64
	global_store_dword v162, v52, s[4:5] offset:128
	global_store_dword v162, v36, s[4:5] offset:192
	s_add_u32 s4, s4, 0x1000
	s_addc_u32 s5, s5, 0
	global_store_dword v162, v21, s[4:5]
	global_store_dword v162, v5, s[4:5] offset:64
	global_store_dword v162, v53, s[4:5] offset:128
	global_store_dword v162, v37, s[4:5] offset:192
	s_add_u32 s4, s4, 0x5000
	s_addc_u32 s5, s5, 0
	global_store_dword v162, v22, s[4:5]
	global_store_dword v162, v6, s[4:5] offset:64
	global_store_dword v162, v54, s[4:5] offset:128
	global_store_dword v162, v38, s[4:5] offset:192
	s_add_u32 s4, s4, 0x1000
	s_addc_u32 s5, s5, 0
	global_store_dword v162, v23, s[4:5]
	global_store_dword v162, v7, s[4:5] offset:64
	global_store_dword v162, v55, s[4:5] offset:128
	global_store_dword v162, v39, s[4:5] offset:192
	s_add_u32 s4, s4, 0x1000
	s_addc_u32 s5, s5, 0
	global_store_dword v162, v24, s[4:5]
	global_store_dword v162, v8, s[4:5] offset:64
	global_store_dword v162, v56, s[4:5] offset:128
	global_store_dword v162, v40, s[4:5] offset:192
	s_add_u32 s4, s4, 0x1000
	s_addc_u32 s5, s5, 0
	global_store_dword v162, v25, s[4:5]
	global_store_dword v162, v9, s[4:5] offset:64
	global_store_dword v162, v57, s[4:5] offset:128
	global_store_dword v162, v41, s[4:5] offset:192
	s_add_u32 s4, s4, 0x5000
	s_addc_u32 s5, s5, 0
	global_store_dword v162, v26, s[4:5]
	global_store_dword v162, v10, s[4:5] offset:64
	global_store_dword v162, v58, s[4:5] offset:128
	global_store_dword v162, v42, s[4:5] offset:192
	s_add_u32 s4, s4, 0x1000
	s_addc_u32 s5, s5, 0
	global_store_dword v162, v27, s[4:5]
	global_store_dword v162, v11, s[4:5] offset:64
	global_store_dword v162, v59, s[4:5] offset:128
	global_store_dword v162, v43, s[4:5] offset:192
	s_add_u32 s4, s4, 0x1000
	s_addc_u32 s5, s5, 0
	global_store_dword v162, v28, s[4:5]
	global_store_dword v162, v12, s[4:5] offset:64
	global_store_dword v162, v60, s[4:5] offset:128
	global_store_dword v162, v44, s[4:5] offset:192
	s_add_u32 s4, s4, 0x1000
	s_addc_u32 s5, s5, 0
	global_store_dword v162, v29, s[4:5]
	global_store_dword v162, v13, s[4:5] offset:64
	global_store_dword v162, v61, s[4:5] offset:128
	global_store_dword v162, v45, s[4:5] offset:192
	s_add_u32 s4, s4, 0x5000
	s_addc_u32 s5, s5, 0
	global_store_dword v162, v30, s[4:5]
	global_store_dword v162, v14, s[4:5] offset:64
	global_store_dword v162, v62, s[4:5] offset:128
	global_store_dword v162, v46, s[4:5] offset:192
	s_add_u32 s4, s4, 0x1000
	s_addc_u32 s5, s5, 0
	global_store_dword v162, v31, s[4:5]
	global_store_dword v162, v15, s[4:5] offset:64
	global_store_dword v162, v63, s[4:5] offset:128
	global_store_dword v162, v47, s[4:5] offset:192
	s_add_u32 s4, s4, 0x1000
	s_addc_u32 s5, s5, 0
	global_store_dword v162, v32, s[4:5]
	global_store_dword v162, v16, s[4:5] offset:64
	global_store_dword v162, v64, s[4:5] offset:128
	global_store_dword v162, v48, s[4:5] offset:192
	s_add_u32 s4, s4, 0x1000
	s_addc_u32 s5, s5, 0
	global_store_dword v162, v33, s[4:5]
	global_store_dword v162, v17, s[4:5] offset:64
	global_store_dword v162, v65, s[4:5] offset:128
	global_store_dword v162, v49, s[4:5] offset:192
	s_mov_b64 exec, -1
	s_mov_b64 s[4:5], -1
	s_branch .LBB0_603
